# skip the initial cooperative grid.sync (orders nothing; the XCD barrier self-synchronises on posted counts)
# speedup vs baseline: 1.0007x; 1.0007x over previous
.LBB0_5:
	s_or_b64 exec, exec, s[2:3]
	v_lshrrev_b32_e32 v1, 20, v0
	v_lshrrev_b32_e32 v0, 10, v0
	v_or_b32_e32 v0, v0, v1
	s_movk_i32 s2, 0x3ff
	v_and_or_b32 v0, v0, s2, v210
	v_cmp_eq_u32_e32 vcc, 0, v0
	s_barrier
	s_and_saveexec_b64 s[2:3], vcc
	s_branch .LBB0_15
	buffer_wbl2 sc1
	s_waitcnt vmcnt(0)
	s_load_dwordx2 s[4:5], s[4:5], 0x58
	v_mov_b32_e32 v2, 0
	s_mov_b64 s[8:9], exec
	v_mbcnt_lo_u32_b32 v1, s8, 0
	v_mbcnt_hi_u32_b32 v1, s9, v1
	s_waitcnt lgkmcnt(0)
	global_load_dword v0, v2, s[4:5] offset:40
	v_cmp_eq_u32_e32 vcc, 0, v1
	s_and_saveexec_b64 s[14:15], vcc
	s_cbranch_execz .LBB0_8
	s_bcnt1_i32_b64 s8, s[8:9]
	v_mov_b32_e32 v3, s8
	global_atomic_add v3, v2, v3, s[4:5] offset:32 sc0
